# v63 + P4/P9 SwiGLU body: (2 v_mov + v_pk_mul broadcast) -> 2 v_mul_f32 at 32 sites per phase
# speedup vs baseline: 1.0182x; 1.0028x over previous
.Lrstd_done_p4:
	v_or_b32_e32 v160, 16, v162
	v_or_b32_e32 v156, 32, v162
	v_or_b32_e32 v154, 48, v162
	v_add_u32_e32 v148, 0x80, v162
	v_add_u32_e32 v152, 0x90, v162
	v_add_u32_e32 v150, 0xa0, v162
	v_add_u32_e32 v146, 0xb0, v162
	v_mul_f32_e32 v180, v120, v176
	v_mul_f32_e32 v181, v124, v176
	v_mov_b32_e32 v124, v121
	v_mul_f32_e32 v120, 0xbfb8aa3b, v181
	v_exp_f32_e32 v147, v120
	v_pk_mul_f32 v[120:121], v[124:125], v[176:177] op_sel_hi:[1,0]
	s_andn2_b64 vcc, exec, s[6:7]
	v_mul_f32_e32 v124, 0xbfb8aa3b, v121
	v_exp_f32_e32 v125, v124
	v_add_f32_e32 v147, 1.0, v147
	v_rcp_f32_e32 v147, v147
	v_lshl_or_b32 v124, s33, 7, v167
	v_add_f32_e32 v125, 1.0, v125
	v_rcp_f32_e32 v149, v125
	v_mul_f32_e32 v147, v181, v147
	v_mul_f32_e32 v147, v180, v147
	v_mul_f32_e32 v180, v122, v176
	v_mul_f32_e32 v181, v126, v176
	v_mov_b32_e32 v126, v123
	v_mul_f32_e32 v122, 0xbfb8aa3b, v181
	v_mul_f32_e32 v121, v121, v149
	v_exp_f32_e32 v149, v122
	v_pk_mul_f32 v[122:123], v[126:127], v[176:177] op_sel_hi:[1,0]
	v_mul_f32_e32 v127, v120, v121
	v_mul_f32_e32 v126, 0xbfb8aa3b, v123
	v_exp_f32_e32 v126, v126
	v_add_f32_e32 v120, 1.0, v149
	v_rcp_f32_e32 v149, v120
	v_add_f32_e32 v120, 1.0, v126
	v_rcp_f32_e32 v126, v120
	v_mul_f32_e32 v120, v112, v176
	v_mul_f32_e32 v121, v116, v176
	v_mul_f32_e32 v116, v181, v149
	v_mul_f32_e32 v112, 0xbfb8aa3b, v121
	v_exp_f32_e32 v112, v112
	v_mul_f32_e32 v149, v180, v116
	v_mov_b32_e32 v116, v113
	v_mul_f32_e32 v123, v123, v126
	v_add_f32_e32 v112, 1.0, v112
	v_rcp_f32_e32 v126, v112
	v_pk_mul_f32 v[112:113], v[116:117], v[176:177] op_sel_hi:[1,0]
	v_mul_f32_e32 v122, v122, v123
	v_mul_f32_e32 v116, 0xbfb8aa3b, v113
	v_exp_f32_e32 v116, v116
	v_mul_f32_e32 v117, v121, v126
	v_mul_f32_e32 v120, v120, v117
	v_add_f32_e32 v116, 1.0, v116
	v_rcp_f32_e32 v121, v116
	v_mul_f32_e32 v116, v114, v176
	v_mul_f32_e32 v117, v118, v176
	v_mov_b32_e32 v118, v115
	v_mul_f32_e32 v114, 0xbfb8aa3b, v117
	v_exp_f32_e32 v123, v114
	v_pk_mul_f32 v[114:115], v[118:119], v[176:177] op_sel_hi:[1,0]
	v_mul_f32_e32 v113, v113, v121
	v_mul_f32_e32 v118, 0xbfb8aa3b, v115
	v_exp_f32_e32 v118, v118
	v_add_f32_e32 v119, 1.0, v123
	v_rcp_f32_e32 v119, v119
	v_mul_f32_e32 v112, v112, v113
	v_add_f32_e32 v118, 1.0, v118
	v_rcp_f32_e32 v118, v118
	v_mul_f32_e32 v113, v117, v119
	v_mul_f32_e32 v113, v116, v113
	v_cvt_pk_bf16_f32 v116, v147, v127
	v_cvt_pk_bf16_f32 v117, v149, v122
	v_mul_f32_e32 v115, v115, v118
	v_mul_f32_e32 v122, v104, v174
	v_mul_f32_e32 v123, v108, v174
	v_ashrrev_i32_e32 v125, 31, v124
	v_mul_f32_e32 v114, v114, v115
	v_mul_f32_e32 v104, 0xbfb8aa3b, v123
	v_cvt_pk_bf16_f32 v118, v120, v112
	v_cvt_pk_bf16_f32 v119, v113, v114
	v_lshlrev_b64 v[114:115], 1, v[124:125]
	v_exp_f32_e32 v124, v104
	v_mov_b32_e32 v108, v105
	v_mov_b64_e32 v[112:113], s[26:27]
	v_pk_mul_f32 v[104:105], v[108:109], v[174:175] op_sel_hi:[1,0]
	v_mad_i64_i32 v[120:121], s[4:5], v162, s52, v[112:113]
	v_mul_f32_e32 v108, 0xbfb8aa3b, v105
	v_exp_f32_e32 v125, v108
	v_lshl_add_u64 v[108:109], v[120:121], 0, v[114:115]
	v_add_f32_e32 v120, 1.0, v124
	v_rcp_f32_e32 v120, v120
	global_store_dwordx4 v[108:109], v[116:119], off
	v_add_f32_e32 v121, 1.0, v125
	v_mul_f32_e32 v108, v123, v120
	v_mul_f32_e32 v116, v122, v108
	v_mul_f32_e32 v108, v106, v174
	v_mul_f32_e32 v109, v110, v174
	v_mov_b32_e32 v110, v107
	v_mul_f32_e32 v106, 0xbfb8aa3b, v109
	v_rcp_f32_e32 v121, v121
	v_exp_f32_e32 v117, v106
	v_pk_mul_f32 v[106:107], v[110:111], v[174:175] op_sel_hi:[1,0]
	v_mul_f32_e32 v105, v105, v121
	v_mul_f32_e32 v110, 0xbfb8aa3b, v107
	v_exp_f32_e32 v110, v110
	v_mul_f32_e32 v111, v104, v105
	v_add_f32_e32 v104, 1.0, v117
	v_rcp_f32_e32 v117, v104
	v_add_f32_e32 v104, 1.0, v110
	v_rcp_f32_e32 v110, v104
	v_mul_f32_e32 v104, v96, v174
	v_mul_f32_e32 v105, v100, v174
	v_mul_f32_e32 v100, v109, v117
	v_mul_f32_e32 v96, 0xbfb8aa3b, v105
	v_exp_f32_e32 v96, v96
	v_mul_f32_e32 v108, v108, v100
	v_mov_b32_e32 v100, v97
	v_mul_f32_e32 v107, v107, v110
	v_add_f32_e32 v96, 1.0, v96
	v_rcp_f32_e32 v109, v96
	v_pk_mul_f32 v[96:97], v[100:101], v[174:175] op_sel_hi:[1,0]
	v_mul_f32_e32 v106, v106, v107
	v_mul_f32_e32 v100, 0xbfb8aa3b, v97
	v_exp_f32_e32 v100, v100
	v_mul_f32_e32 v101, v105, v109
	v_mul_f32_e32 v104, v104, v101
	v_add_f32_e32 v100, 1.0, v100
	v_rcp_f32_e32 v105, v100
	v_mul_f32_e32 v100, v98, v174
	v_mul_f32_e32 v101, v102, v174
	v_mov_b32_e32 v102, v99
	v_mul_f32_e32 v98, 0xbfb8aa3b, v101
	v_exp_f32_e32 v107, v98
	v_pk_mul_f32 v[98:99], v[102:103], v[174:175] op_sel_hi:[1,0]
	v_mul_f32_e32 v97, v97, v105
	v_mul_f32_e32 v102, 0xbfb8aa3b, v99
	v_exp_f32_e32 v102, v102
	v_add_f32_e32 v103, 1.0, v107
	v_rcp_f32_e32 v103, v103
	v_mul_f32_e32 v105, v96, v97
	v_add_f32_e32 v102, 1.0, v102
	v_rcp_f32_e32 v102, v102
	v_mul_f32_e32 v96, v101, v103
	v_mul_f32_e32 v100, v100, v96
	v_mul_f32_e32 v96, v99, v102
	v_mul_f32_e32 v102, v88, v172
	v_mul_f32_e32 v103, v92, v172
	v_mul_f32_e32 v99, v98, v96
	v_mul_f32_e32 v88, 0xbfb8aa3b, v103
	v_cvt_pk_bf16_f32 v96, v116, v111
	v_cvt_pk_bf16_f32 v97, v108, v106
	v_cvt_pk_bf16_f32 v98, v104, v105
	v_exp_f32_e32 v104, v88
	v_mov_b32_e32 v92, v89
	v_pk_mul_f32 v[88:89], v[92:93], v[172:173] op_sel_hi:[1,0]
	v_cvt_pk_bf16_f32 v99, v100, v99
	v_mad_i64_i32 v[100:101], s[4:5], v160, s52, v[112:113]
	v_mul_f32_e32 v92, 0xbfb8aa3b, v89
	v_exp_f32_e32 v105, v92
	v_lshl_add_u64 v[92:93], v[100:101], 0, v[114:115]
	v_add_f32_e32 v100, 1.0, v104
	v_rcp_f32_e32 v100, v100
	global_store_dwordx4 v[92:93], v[96:99], off
	v_add_f32_e32 v101, 1.0, v105
	v_mul_f32_e32 v92, v103, v100
	v_mul_f32_e32 v96, v102, v92
	v_mul_f32_e32 v92, v90, v172
	v_mul_f32_e32 v93, v94, v172
	v_mov_b32_e32 v94, v91
	v_mul_f32_e32 v90, 0xbfb8aa3b, v93
	v_rcp_f32_e32 v101, v101
	v_exp_f32_e32 v97, v90
	v_pk_mul_f32 v[90:91], v[94:95], v[172:173] op_sel_hi:[1,0]
	v_mul_f32_e32 v89, v89, v101
	v_mul_f32_e32 v94, 0xbfb8aa3b, v91
	v_exp_f32_e32 v94, v94
	v_mul_f32_e32 v95, v88, v89
	v_add_f32_e32 v88, 1.0, v97
	v_rcp_f32_e32 v97, v88
	v_add_f32_e32 v88, 1.0, v94
	v_rcp_f32_e32 v94, v88
	v_mul_f32_e32 v88, v80, v172
	v_mul_f32_e32 v89, v84, v172
	v_mul_f32_e32 v84, v93, v97
	v_mul_f32_e32 v80, 0xbfb8aa3b, v89
	v_exp_f32_e32 v80, v80
	v_mul_f32_e32 v92, v92, v84
	v_mov_b32_e32 v84, v81
	v_mul_f32_e32 v91, v91, v94
	v_add_f32_e32 v80, 1.0, v80
	v_rcp_f32_e32 v93, v80
	v_pk_mul_f32 v[80:81], v[84:85], v[172:173] op_sel_hi:[1,0]
	v_mul_f32_e32 v90, v90, v91
	v_mul_f32_e32 v84, 0xbfb8aa3b, v81
	v_exp_f32_e32 v84, v84
	v_mul_f32_e32 v85, v89, v93
	v_mul_f32_e32 v88, v88, v85
	v_add_f32_e32 v84, 1.0, v84
	v_rcp_f32_e32 v89, v84
	v_mul_f32_e32 v84, v82, v172
	v_mul_f32_e32 v85, v86, v172
	v_mov_b32_e32 v86, v83
	v_mul_f32_e32 v82, 0xbfb8aa3b, v85
	v_exp_f32_e32 v91, v82
	v_pk_mul_f32 v[82:83], v[86:87], v[172:173] op_sel_hi:[1,0]
	v_mul_f32_e32 v81, v81, v89
	v_mul_f32_e32 v86, 0xbfb8aa3b, v83
	v_exp_f32_e32 v86, v86
	v_add_f32_e32 v87, 1.0, v91
	v_rcp_f32_e32 v87, v87
	v_mul_f32_e32 v89, v80, v81
	v_add_f32_e32 v86, 1.0, v86
	v_rcp_f32_e32 v86, v86
	v_mul_f32_e32 v80, v85, v87
	v_mul_f32_e32 v84, v84, v80
	v_mul_f32_e32 v80, v83, v86
	v_mul_f32_e32 v86, v72, v170
	v_mul_f32_e32 v87, v76, v170
	v_mul_f32_e32 v83, v82, v80
	v_mul_f32_e32 v72, 0xbfb8aa3b, v87
	v_cvt_pk_bf16_f32 v80, v96, v95
	v_cvt_pk_bf16_f32 v81, v92, v90
	v_cvt_pk_bf16_f32 v82, v88, v89
	v_exp_f32_e32 v88, v72
	v_mov_b32_e32 v76, v73
	v_pk_mul_f32 v[72:73], v[76:77], v[170:171] op_sel_hi:[1,0]
	v_cvt_pk_bf16_f32 v83, v84, v83
	v_mad_i64_i32 v[84:85], s[4:5], v156, s52, v[112:113]
	v_mul_f32_e32 v76, 0xbfb8aa3b, v73
	v_exp_f32_e32 v89, v76
	v_lshl_add_u64 v[76:77], v[84:85], 0, v[114:115]
	v_add_f32_e32 v84, 1.0, v88
	v_rcp_f32_e32 v84, v84
	global_store_dwordx4 v[76:77], v[80:83], off
	v_add_f32_e32 v85, 1.0, v89
	v_mul_f32_e32 v76, v87, v84
	v_mul_f32_e32 v80, v86, v76
	v_mul_f32_e32 v76, v74, v170
	v_mul_f32_e32 v77, v78, v170
	v_mov_b32_e32 v78, v75
	v_mul_f32_e32 v74, 0xbfb8aa3b, v77
	v_rcp_f32_e32 v85, v85
	v_exp_f32_e32 v81, v74
	v_pk_mul_f32 v[74:75], v[78:79], v[170:171] op_sel_hi:[1,0]
	v_mul_f32_e32 v73, v73, v85
	v_mul_f32_e32 v78, 0xbfb8aa3b, v75
	v_exp_f32_e32 v78, v78
	v_mul_f32_e32 v79, v72, v73
	v_add_f32_e32 v72, 1.0, v81
	v_rcp_f32_e32 v81, v72
	v_add_f32_e32 v72, 1.0, v78
	v_rcp_f32_e32 v78, v72
	v_mul_f32_e32 v72, v64, v170
	v_mul_f32_e32 v73, v68, v170
	v_mul_f32_e32 v68, v77, v81
	v_mul_f32_e32 v64, 0xbfb8aa3b, v73
	v_exp_f32_e32 v64, v64
	v_mul_f32_e32 v76, v76, v68
	v_mov_b32_e32 v68, v65
	v_mul_f32_e32 v75, v75, v78
	v_add_f32_e32 v64, 1.0, v64
	v_rcp_f32_e32 v77, v64
	v_pk_mul_f32 v[64:65], v[68:69], v[170:171] op_sel_hi:[1,0]
	v_mul_f32_e32 v74, v74, v75
	v_mul_f32_e32 v68, 0xbfb8aa3b, v65
	v_exp_f32_e32 v68, v68
	v_mul_f32_e32 v69, v73, v77
	v_mul_f32_e32 v72, v72, v69
	v_add_f32_e32 v68, 1.0, v68
	v_rcp_f32_e32 v73, v68
	v_mul_f32_e32 v68, v66, v170
	v_mul_f32_e32 v69, v70, v170
	v_mov_b32_e32 v70, v67
	v_mul_f32_e32 v66, 0xbfb8aa3b, v69
	v_exp_f32_e32 v75, v66
	v_pk_mul_f32 v[66:67], v[70:71], v[170:171] op_sel_hi:[1,0]
	v_mul_f32_e32 v65, v65, v73
	v_mul_f32_e32 v70, 0xbfb8aa3b, v67
	v_exp_f32_e32 v70, v70
	v_add_f32_e32 v71, 1.0, v75
	v_rcp_f32_e32 v71, v71
	v_mul_f32_e32 v73, v64, v65
	v_add_f32_e32 v70, 1.0, v70
	v_rcp_f32_e32 v70, v70
	v_mul_f32_e32 v64, v69, v71
	v_mul_f32_e32 v68, v68, v64
	v_mul_f32_e32 v64, v67, v70
	v_mul_f32_e32 v70, v56, v168
	v_mul_f32_e32 v71, v60, v168
	v_mul_f32_e32 v67, v66, v64
	v_mul_f32_e32 v56, 0xbfb8aa3b, v71
	v_cvt_pk_bf16_f32 v64, v80, v79
	v_cvt_pk_bf16_f32 v65, v76, v74
	v_cvt_pk_bf16_f32 v66, v72, v73
	v_exp_f32_e32 v72, v56
	v_mov_b32_e32 v60, v57
	v_pk_mul_f32 v[56:57], v[60:61], v[168:169] op_sel_hi:[1,0]
	v_cvt_pk_bf16_f32 v67, v68, v67
	v_mad_i64_i32 v[68:69], s[4:5], v154, s52, v[112:113]
	v_mul_f32_e32 v60, 0xbfb8aa3b, v57
	v_exp_f32_e32 v73, v60
	v_lshl_add_u64 v[60:61], v[68:69], 0, v[114:115]
	v_add_f32_e32 v68, 1.0, v72
	v_rcp_f32_e32 v68, v68
	global_store_dwordx4 v[60:61], v[64:67], off
	v_add_f32_e32 v69, 1.0, v73
	v_mul_f32_e32 v60, v71, v68
	v_mul_f32_e32 v64, v70, v60
	v_mul_f32_e32 v60, v58, v168
	v_mul_f32_e32 v61, v62, v168
	v_mov_b32_e32 v62, v59
	v_mul_f32_e32 v58, 0xbfb8aa3b, v61
	v_rcp_f32_e32 v69, v69
	v_exp_f32_e32 v65, v58
	v_pk_mul_f32 v[58:59], v[62:63], v[168:169] op_sel_hi:[1,0]
	v_mul_f32_e32 v57, v57, v69
	v_mul_f32_e32 v62, 0xbfb8aa3b, v59
	v_exp_f32_e32 v62, v62
	v_mul_f32_e32 v63, v56, v57
	v_add_f32_e32 v56, 1.0, v65
	v_rcp_f32_e32 v65, v56
	v_add_f32_e32 v56, 1.0, v62
	v_rcp_f32_e32 v62, v56
	v_mul_f32_e32 v56, v48, v168
	v_mul_f32_e32 v57, v52, v168
	v_mul_f32_e32 v52, v61, v65
	v_mul_f32_e32 v48, 0xbfb8aa3b, v57
	v_exp_f32_e32 v48, v48
	v_mul_f32_e32 v60, v60, v52
	v_mov_b32_e32 v52, v49
	v_mul_f32_e32 v59, v59, v62
	v_add_f32_e32 v48, 1.0, v48
	v_rcp_f32_e32 v61, v48
	v_pk_mul_f32 v[48:49], v[52:53], v[168:169] op_sel_hi:[1,0]
	v_mul_f32_e32 v58, v58, v59
	v_mul_f32_e32 v52, 0xbfb8aa3b, v49
	v_exp_f32_e32 v52, v52
	v_mul_f32_e32 v53, v57, v61
	v_mul_f32_e32 v56, v56, v53
	v_add_f32_e32 v52, 1.0, v52
	v_rcp_f32_e32 v57, v52
	v_mul_f32_e32 v52, v50, v168
	v_mul_f32_e32 v53, v54, v168
	v_mov_b32_e32 v54, v51
	v_mul_f32_e32 v50, 0xbfb8aa3b, v53
	v_exp_f32_e32 v59, v50
	v_pk_mul_f32 v[50:51], v[54:55], v[168:169] op_sel_hi:[1,0]
	v_mul_f32_e32 v49, v49, v57
	v_mul_f32_e32 v54, 0xbfb8aa3b, v51
	v_exp_f32_e32 v54, v54
	v_add_f32_e32 v55, 1.0, v59
	v_rcp_f32_e32 v55, v55
	v_mul_f32_e32 v57, v48, v49
	v_add_f32_e32 v54, 1.0, v54
	v_rcp_f32_e32 v54, v54
	v_mul_f32_e32 v48, v53, v55
	v_mul_f32_e32 v52, v52, v48
	v_mul_f32_e32 v48, v51, v54
	v_mul_f32_e32 v54, v40, v166
	v_mul_f32_e32 v55, v44, v166
	v_mul_f32_e32 v51, v50, v48
	v_mul_f32_e32 v40, 0xbfb8aa3b, v55
	v_cvt_pk_bf16_f32 v48, v64, v63
	v_cvt_pk_bf16_f32 v49, v60, v58
	v_cvt_pk_bf16_f32 v50, v56, v57
	v_exp_f32_e32 v56, v40
	v_mov_b32_e32 v44, v41
	v_pk_mul_f32 v[40:41], v[44:45], v[166:167] op_sel_hi:[1,0]
	v_cvt_pk_bf16_f32 v51, v52, v51
	v_mad_i64_i32 v[52:53], s[4:5], v148, s52, v[112:113]
	v_mul_f32_e32 v44, 0xbfb8aa3b, v41
	v_exp_f32_e32 v57, v44
	v_lshl_add_u64 v[44:45], v[52:53], 0, v[114:115]
	v_add_f32_e32 v52, 1.0, v56
	v_rcp_f32_e32 v52, v52
	global_store_dwordx4 v[44:45], v[48:51], off
	v_add_f32_e32 v53, 1.0, v57
	v_mul_f32_e32 v44, v55, v52
	v_mul_f32_e32 v48, v54, v44
	v_mul_f32_e32 v44, v42, v166
	v_mul_f32_e32 v45, v46, v166
	v_mov_b32_e32 v46, v43
	v_mul_f32_e32 v42, 0xbfb8aa3b, v45
	v_rcp_f32_e32 v53, v53
	v_exp_f32_e32 v49, v42
	v_pk_mul_f32 v[42:43], v[46:47], v[166:167] op_sel_hi:[1,0]
	v_mul_f32_e32 v41, v41, v53
	v_mul_f32_e32 v46, 0xbfb8aa3b, v43
	v_exp_f32_e32 v46, v46
	v_mul_f32_e32 v47, v40, v41
	v_add_f32_e32 v40, 1.0, v49
	v_rcp_f32_e32 v49, v40
	v_add_f32_e32 v40, 1.0, v46
	v_rcp_f32_e32 v46, v40
	v_mul_f32_e32 v40, v32, v166
	v_mul_f32_e32 v41, v36, v166
	v_mul_f32_e32 v36, v45, v49
	v_mul_f32_e32 v32, 0xbfb8aa3b, v41
	v_exp_f32_e32 v32, v32
	v_mul_f32_e32 v44, v44, v36
	v_mov_b32_e32 v36, v33
	v_mul_f32_e32 v43, v43, v46
	v_add_f32_e32 v32, 1.0, v32
	v_rcp_f32_e32 v45, v32
	v_pk_mul_f32 v[32:33], v[36:37], v[166:167] op_sel_hi:[1,0]
	v_mul_f32_e32 v42, v42, v43
	v_mul_f32_e32 v36, 0xbfb8aa3b, v33
	v_exp_f32_e32 v36, v36
	v_mul_f32_e32 v37, v41, v45
	v_mul_f32_e32 v40, v40, v37
	v_add_f32_e32 v36, 1.0, v36
	v_rcp_f32_e32 v41, v36
	v_mul_f32_e32 v36, v34, v166
	v_mul_f32_e32 v37, v38, v166
	v_mov_b32_e32 v38, v35
	v_mul_f32_e32 v34, 0xbfb8aa3b, v37
	v_exp_f32_e32 v43, v34
	v_pk_mul_f32 v[34:35], v[38:39], v[166:167] op_sel_hi:[1,0]
	v_mul_f32_e32 v33, v33, v41
	v_mul_f32_e32 v38, 0xbfb8aa3b, v35
	v_exp_f32_e32 v38, v38
	v_add_f32_e32 v39, 1.0, v43
	v_rcp_f32_e32 v39, v39
	v_mul_f32_e32 v41, v32, v33
	v_add_f32_e32 v38, 1.0, v38
	v_rcp_f32_e32 v38, v38
	v_mul_f32_e32 v32, v37, v39
	v_mul_f32_e32 v36, v36, v32
	v_mul_f32_e32 v32, v35, v38
	v_mul_f32_e32 v38, v24, v164
	v_mul_f32_e32 v39, v28, v164
	v_mul_f32_e32 v35, v34, v32
	v_mul_f32_e32 v24, 0xbfb8aa3b, v39
	v_cvt_pk_bf16_f32 v32, v48, v47
	v_cvt_pk_bf16_f32 v33, v44, v42
	v_cvt_pk_bf16_f32 v34, v40, v41
	v_exp_f32_e32 v40, v24
	v_mov_b32_e32 v28, v25
	v_pk_mul_f32 v[24:25], v[28:29], v[164:165] op_sel_hi:[1,0]
	v_cvt_pk_bf16_f32 v35, v36, v35
	v_mad_i64_i32 v[36:37], s[4:5], v152, s52, v[112:113]
	v_mul_f32_e32 v28, 0xbfb8aa3b, v25
	v_exp_f32_e32 v41, v28
	v_lshl_add_u64 v[28:29], v[36:37], 0, v[114:115]
	v_add_f32_e32 v36, 1.0, v40
	v_rcp_f32_e32 v36, v36
	global_store_dwordx4 v[28:29], v[32:35], off
	v_add_f32_e32 v37, 1.0, v41
	v_mul_f32_e32 v28, v39, v36
	v_mul_f32_e32 v32, v38, v28
	v_mul_f32_e32 v28, v26, v164
	v_mul_f32_e32 v29, v30, v164
	v_mov_b32_e32 v30, v27
	v_mul_f32_e32 v26, 0xbfb8aa3b, v29
	v_rcp_f32_e32 v37, v37
	v_exp_f32_e32 v33, v26
	v_pk_mul_f32 v[26:27], v[30:31], v[164:165] op_sel_hi:[1,0]
	v_mul_f32_e32 v25, v25, v37
	v_mul_f32_e32 v30, 0xbfb8aa3b, v27
	v_exp_f32_e32 v30, v30
	v_mul_f32_e32 v31, v24, v25
	v_add_f32_e32 v24, 1.0, v33
	v_rcp_f32_e32 v33, v24
	v_add_f32_e32 v24, 1.0, v30
	v_rcp_f32_e32 v30, v24
	v_mul_f32_e32 v24, v16, v164
	v_mul_f32_e32 v25, v20, v164
	v_mul_f32_e32 v20, v29, v33
	v_mul_f32_e32 v16, 0xbfb8aa3b, v25
	v_exp_f32_e32 v16, v16
	v_mul_f32_e32 v28, v28, v20
	v_mov_b32_e32 v20, v17
	v_mul_f32_e32 v27, v27, v30
	v_add_f32_e32 v16, 1.0, v16
	v_rcp_f32_e32 v29, v16
	v_pk_mul_f32 v[16:17], v[20:21], v[164:165] op_sel_hi:[1,0]
	v_mul_f32_e32 v26, v26, v27
	v_mul_f32_e32 v20, 0xbfb8aa3b, v17
	v_exp_f32_e32 v20, v20
	v_mul_f32_e32 v21, v25, v29
	v_mul_f32_e32 v24, v24, v21
	v_add_f32_e32 v20, 1.0, v20
	v_rcp_f32_e32 v25, v20
	v_mul_f32_e32 v20, v18, v164
	v_mul_f32_e32 v21, v22, v164
	v_mov_b32_e32 v22, v19
	v_mul_f32_e32 v18, 0xbfb8aa3b, v21
	v_exp_f32_e32 v27, v18
	v_pk_mul_f32 v[18:19], v[22:23], v[164:165] op_sel_hi:[1,0]
	v_mul_f32_e32 v17, v17, v25
	v_mul_f32_e32 v22, 0xbfb8aa3b, v19
	v_exp_f32_e32 v22, v22
	v_add_f32_e32 v23, 1.0, v27
	v_rcp_f32_e32 v23, v23
	v_mul_f32_e32 v25, v16, v17
	v_add_f32_e32 v22, 1.0, v22
	v_rcp_f32_e32 v22, v22
	v_mul_f32_e32 v16, v21, v23
	v_mul_f32_e32 v20, v20, v16
	v_mul_f32_e32 v16, v19, v22
	v_mul_f32_e32 v22, v8, v158
	v_mul_f32_e32 v23, v12, v158
	v_mul_f32_e32 v19, v18, v16
	v_mul_f32_e32 v8, 0xbfb8aa3b, v23
	v_cvt_pk_bf16_f32 v16, v32, v31
	v_cvt_pk_bf16_f32 v17, v28, v26
	v_cvt_pk_bf16_f32 v18, v24, v25
	v_exp_f32_e32 v24, v8
	v_mov_b32_e32 v12, v9
	v_pk_mul_f32 v[8:9], v[12:13], v[158:159] op_sel_hi:[1,0]
	v_cvt_pk_bf16_f32 v19, v20, v19
	v_mad_i64_i32 v[20:21], s[4:5], v150, s52, v[112:113]
	v_mul_f32_e32 v12, 0xbfb8aa3b, v9
	v_exp_f32_e32 v25, v12
	v_lshl_add_u64 v[12:13], v[20:21], 0, v[114:115]
	v_add_f32_e32 v20, 1.0, v24
	v_rcp_f32_e32 v20, v20
	global_store_dwordx4 v[12:13], v[16:19], off
	v_add_f32_e32 v21, 1.0, v25
	v_mul_f32_e32 v12, v23, v20
	v_mul_f32_e32 v16, v22, v12
	v_mul_f32_e32 v12, v10, v158
	v_mul_f32_e32 v13, v14, v158
	v_mov_b32_e32 v14, v11
	v_mul_f32_e32 v10, 0xbfb8aa3b, v13
	v_rcp_f32_e32 v21, v21
	v_exp_f32_e32 v17, v10
	v_pk_mul_f32 v[10:11], v[14:15], v[158:159] op_sel_hi:[1,0]
	v_mul_f32_e32 v9, v9, v21
	v_mul_f32_e32 v14, 0xbfb8aa3b, v11
	v_exp_f32_e32 v14, v14
	v_mul_f32_e32 v15, v8, v9
	v_add_f32_e32 v8, 1.0, v17
	v_rcp_f32_e32 v17, v8
	v_add_f32_e32 v8, 1.0, v14
	v_rcp_f32_e32 v14, v8
	v_mul_f32_e32 v8, v0, v158
	v_mul_f32_e32 v9, v4, v158
	v_mul_f32_e32 v4, v13, v17
	v_mul_f32_e32 v0, 0xbfb8aa3b, v9
	v_exp_f32_e32 v0, v0
	v_mul_f32_e32 v12, v12, v4
	v_mov_b32_e32 v4, v1
	v_mul_f32_e32 v11, v11, v14
	v_add_f32_e32 v0, 1.0, v0
	v_rcp_f32_e32 v13, v0
	v_pk_mul_f32 v[0:1], v[4:5], v[158:159] op_sel_hi:[1,0]
	v_mul_f32_e32 v10, v10, v11
	v_mul_f32_e32 v4, 0xbfb8aa3b, v1
	v_exp_f32_e32 v4, v4
	v_mul_f32_e32 v5, v9, v13
	v_mul_f32_e32 v8, v8, v5
	v_add_f32_e32 v4, 1.0, v4
	v_rcp_f32_e32 v9, v4
	v_mul_f32_e32 v4, v2, v158
	v_mul_f32_e32 v5, v6, v158
	v_mov_b32_e32 v6, v3
	v_mul_f32_e32 v2, 0xbfb8aa3b, v5
	v_exp_f32_e32 v11, v2
	v_pk_mul_f32 v[2:3], v[6:7], v[158:159] op_sel_hi:[1,0]
	v_mul_f32_e32 v1, v1, v9
	v_mul_f32_e32 v6, 0xbfb8aa3b, v3
	v_exp_f32_e32 v6, v6
	v_add_f32_e32 v7, 1.0, v11
	v_rcp_f32_e32 v7, v7
	v_mul_f32_e32 v9, v0, v1
	v_add_f32_e32 v6, 1.0, v6
	v_rcp_f32_e32 v6, v6
	v_mul_f32_e32 v0, v5, v7
	v_mul_f32_e32 v4, v4, v0
	v_mul_f32_e32 v0, v3, v6
	v_mul_f32_e32 v3, v2, v0
	v_cvt_pk_bf16_f32 v0, v16, v15
	v_cvt_pk_bf16_f32 v1, v12, v10
	v_cvt_pk_bf16_f32 v2, v8, v9
	v_cvt_pk_bf16_f32 v3, v4, v3
	v_mad_i64_i32 v[4:5], s[4:5], v146, s52, v[112:113]
	v_lshl_add_u64 v[4:5], v[4:5], 0, v[114:115]
	s_mov_b64 s[4:5], -1
	global_store_dwordx4 v[4:5], v[0:3], off
	s_cbranch_vccnz .LBB0_479
	s_andn2_b64 vcc, exec, s[16:17]
	s_cbranch_vccnz .LBB0_478
	s_mov_b32 s90, 1
	s_branch .LBB0_478

.Lrstd_done_p9:
	v_or_b32_e32 v160, 16, v162
	v_or_b32_e32 v156, 32, v162
	v_or_b32_e32 v154, 48, v162
	v_add_u32_e32 v148, 0x80, v162
	v_add_u32_e32 v152, 0x90, v162
	v_add_u32_e32 v150, 0xa0, v162
	v_add_u32_e32 v146, 0xb0, v162
	v_mul_f32_e32 v178, v120, v176
	v_mul_f32_e32 v179, v124, v176
	v_mov_b32_e32 v124, v121
	v_mul_f32_e32 v120, 0xbfb8aa3b, v179
	v_exp_f32_e32 v147, v120
	v_pk_mul_f32 v[120:121], v[124:125], v[176:177] op_sel_hi:[1,0]
	s_andn2_b64 vcc, exec, s[6:7]
	v_mul_f32_e32 v124, 0xbfb8aa3b, v121
	v_exp_f32_e32 v125, v124
	v_add_f32_e32 v147, 1.0, v147
	v_rcp_f32_e32 v147, v147
	v_lshl_or_b32 v124, s33, 7, v167
	v_add_f32_e32 v125, 1.0, v125
	v_rcp_f32_e32 v149, v125
	v_mul_f32_e32 v147, v179, v147
	v_mul_f32_e32 v147, v178, v147
	v_mul_f32_e32 v178, v122, v176
	v_mul_f32_e32 v179, v126, v176
	v_mov_b32_e32 v126, v123
	v_mul_f32_e32 v122, 0xbfb8aa3b, v179
	v_mul_f32_e32 v121, v121, v149
	v_exp_f32_e32 v149, v122
	v_pk_mul_f32 v[122:123], v[126:127], v[176:177] op_sel_hi:[1,0]
	v_mul_f32_e32 v127, v120, v121
	v_mul_f32_e32 v126, 0xbfb8aa3b, v123
	v_exp_f32_e32 v126, v126
	v_add_f32_e32 v120, 1.0, v149
	v_rcp_f32_e32 v149, v120
	v_add_f32_e32 v120, 1.0, v126
	v_rcp_f32_e32 v126, v120
	v_mul_f32_e32 v120, v112, v176
	v_mul_f32_e32 v121, v116, v176
	v_mul_f32_e32 v116, v179, v149
	v_mul_f32_e32 v112, 0xbfb8aa3b, v121
	v_exp_f32_e32 v112, v112
	v_mul_f32_e32 v149, v178, v116
	v_mov_b32_e32 v116, v113
	v_mul_f32_e32 v123, v123, v126
	v_add_f32_e32 v112, 1.0, v112
	v_rcp_f32_e32 v126, v112
	v_pk_mul_f32 v[112:113], v[116:117], v[176:177] op_sel_hi:[1,0]
	v_mul_f32_e32 v122, v122, v123
	v_mul_f32_e32 v116, 0xbfb8aa3b, v113
	v_exp_f32_e32 v116, v116
	v_mul_f32_e32 v117, v121, v126
	v_mul_f32_e32 v120, v120, v117
	v_add_f32_e32 v116, 1.0, v116
	v_rcp_f32_e32 v121, v116
	v_mul_f32_e32 v116, v114, v176
	v_mul_f32_e32 v117, v118, v176
	v_mov_b32_e32 v118, v115
	v_mul_f32_e32 v114, 0xbfb8aa3b, v117
	v_exp_f32_e32 v123, v114
	v_pk_mul_f32 v[114:115], v[118:119], v[176:177] op_sel_hi:[1,0]
	v_mul_f32_e32 v113, v113, v121
	v_mul_f32_e32 v118, 0xbfb8aa3b, v115
	v_exp_f32_e32 v118, v118
	v_add_f32_e32 v119, 1.0, v123
	v_rcp_f32_e32 v119, v119
	v_mul_f32_e32 v112, v112, v113
	v_add_f32_e32 v118, 1.0, v118
	v_rcp_f32_e32 v118, v118
	v_mul_f32_e32 v113, v117, v119
	v_mul_f32_e32 v113, v116, v113
	v_cvt_pk_bf16_f32 v116, v147, v127
	v_cvt_pk_bf16_f32 v117, v149, v122
	v_mul_f32_e32 v115, v115, v118
	v_mul_f32_e32 v122, v104, v174
	v_mul_f32_e32 v123, v108, v174
	v_ashrrev_i32_e32 v125, 31, v124
	v_mul_f32_e32 v114, v114, v115
	v_mul_f32_e32 v104, 0xbfb8aa3b, v123
	v_cvt_pk_bf16_f32 v118, v120, v112
	v_cvt_pk_bf16_f32 v119, v113, v114
	v_lshlrev_b64 v[114:115], 1, v[124:125]
	v_exp_f32_e32 v124, v104
	v_mov_b32_e32 v108, v105
	v_mov_b64_e32 v[112:113], s[22:23]
	v_pk_mul_f32 v[104:105], v[108:109], v[174:175] op_sel_hi:[1,0]
	v_mad_i64_i32 v[120:121], s[4:5], v162, s51, v[112:113]
	v_mul_f32_e32 v108, 0xbfb8aa3b, v105
	v_exp_f32_e32 v125, v108
	v_lshl_add_u64 v[108:109], v[120:121], 0, v[114:115]
	v_add_f32_e32 v120, 1.0, v124
	v_rcp_f32_e32 v120, v120
	global_store_dwordx4 v[108:109], v[116:119], off
	v_add_f32_e32 v121, 1.0, v125
	v_mul_f32_e32 v108, v123, v120
	v_mul_f32_e32 v116, v122, v108
	v_mul_f32_e32 v108, v106, v174
	v_mul_f32_e32 v109, v110, v174
	v_mov_b32_e32 v110, v107
	v_mul_f32_e32 v106, 0xbfb8aa3b, v109
	v_rcp_f32_e32 v121, v121
	v_exp_f32_e32 v117, v106
	v_pk_mul_f32 v[106:107], v[110:111], v[174:175] op_sel_hi:[1,0]
	v_mul_f32_e32 v105, v105, v121
	v_mul_f32_e32 v110, 0xbfb8aa3b, v107
	v_exp_f32_e32 v110, v110
	v_mul_f32_e32 v111, v104, v105
	v_add_f32_e32 v104, 1.0, v117
	v_rcp_f32_e32 v117, v104
	v_add_f32_e32 v104, 1.0, v110
	v_rcp_f32_e32 v110, v104
	v_mul_f32_e32 v104, v96, v174
	v_mul_f32_e32 v105, v100, v174
	v_mul_f32_e32 v100, v109, v117
	v_mul_f32_e32 v96, 0xbfb8aa3b, v105
	v_exp_f32_e32 v96, v96
	v_mul_f32_e32 v108, v108, v100
	v_mov_b32_e32 v100, v97
	v_mul_f32_e32 v107, v107, v110
	v_add_f32_e32 v96, 1.0, v96
	v_rcp_f32_e32 v109, v96
	v_pk_mul_f32 v[96:97], v[100:101], v[174:175] op_sel_hi:[1,0]
	v_mul_f32_e32 v106, v106, v107
	v_mul_f32_e32 v100, 0xbfb8aa3b, v97
	v_exp_f32_e32 v100, v100
	v_mul_f32_e32 v101, v105, v109
	v_mul_f32_e32 v104, v104, v101
	v_add_f32_e32 v100, 1.0, v100
	v_rcp_f32_e32 v105, v100
	v_mul_f32_e32 v100, v98, v174
	v_mul_f32_e32 v101, v102, v174
	v_mov_b32_e32 v102, v99
	v_mul_f32_e32 v98, 0xbfb8aa3b, v101
	v_exp_f32_e32 v107, v98
	v_pk_mul_f32 v[98:99], v[102:103], v[174:175] op_sel_hi:[1,0]
	v_mul_f32_e32 v97, v97, v105
	v_mul_f32_e32 v102, 0xbfb8aa3b, v99
	v_exp_f32_e32 v102, v102
	v_add_f32_e32 v103, 1.0, v107
	v_rcp_f32_e32 v103, v103
	v_mul_f32_e32 v105, v96, v97
	v_add_f32_e32 v102, 1.0, v102
	v_rcp_f32_e32 v102, v102
	v_mul_f32_e32 v96, v101, v103
	v_mul_f32_e32 v100, v100, v96
	v_mul_f32_e32 v96, v99, v102
	v_mul_f32_e32 v102, v88, v172
	v_mul_f32_e32 v103, v92, v172
	v_mul_f32_e32 v99, v98, v96
	v_mul_f32_e32 v88, 0xbfb8aa3b, v103
	v_cvt_pk_bf16_f32 v96, v116, v111
	v_cvt_pk_bf16_f32 v97, v108, v106
	v_cvt_pk_bf16_f32 v98, v104, v105
	v_exp_f32_e32 v104, v88
	v_mov_b32_e32 v92, v89
	v_pk_mul_f32 v[88:89], v[92:93], v[172:173] op_sel_hi:[1,0]
	v_cvt_pk_bf16_f32 v99, v100, v99
	v_mad_i64_i32 v[100:101], s[4:5], v160, s51, v[112:113]
	v_mul_f32_e32 v92, 0xbfb8aa3b, v89
	v_exp_f32_e32 v105, v92
	v_lshl_add_u64 v[92:93], v[100:101], 0, v[114:115]
	v_add_f32_e32 v100, 1.0, v104
	v_rcp_f32_e32 v100, v100
	global_store_dwordx4 v[92:93], v[96:99], off
	v_add_f32_e32 v101, 1.0, v105
	v_mul_f32_e32 v92, v103, v100
	v_mul_f32_e32 v96, v102, v92
	v_mul_f32_e32 v92, v90, v172
	v_mul_f32_e32 v93, v94, v172
	v_mov_b32_e32 v94, v91
	v_mul_f32_e32 v90, 0xbfb8aa3b, v93
	v_rcp_f32_e32 v101, v101
	v_exp_f32_e32 v97, v90
	v_pk_mul_f32 v[90:91], v[94:95], v[172:173] op_sel_hi:[1,0]
	v_mul_f32_e32 v89, v89, v101
	v_mul_f32_e32 v94, 0xbfb8aa3b, v91
	v_exp_f32_e32 v94, v94
	v_mul_f32_e32 v95, v88, v89
	v_add_f32_e32 v88, 1.0, v97
	v_rcp_f32_e32 v97, v88
	v_add_f32_e32 v88, 1.0, v94
	v_rcp_f32_e32 v94, v88
	v_mul_f32_e32 v88, v80, v172
	v_mul_f32_e32 v89, v84, v172
	v_mul_f32_e32 v84, v93, v97
	v_mul_f32_e32 v80, 0xbfb8aa3b, v89
	v_exp_f32_e32 v80, v80
	v_mul_f32_e32 v92, v92, v84
	v_mov_b32_e32 v84, v81
	v_mul_f32_e32 v91, v91, v94
	v_add_f32_e32 v80, 1.0, v80
	v_rcp_f32_e32 v93, v80
	v_pk_mul_f32 v[80:81], v[84:85], v[172:173] op_sel_hi:[1,0]
	v_mul_f32_e32 v90, v90, v91
	v_mul_f32_e32 v84, 0xbfb8aa3b, v81
	v_exp_f32_e32 v84, v84
	v_mul_f32_e32 v85, v89, v93
	v_mul_f32_e32 v88, v88, v85
	v_add_f32_e32 v84, 1.0, v84
	v_rcp_f32_e32 v89, v84
	v_mul_f32_e32 v84, v82, v172
	v_mul_f32_e32 v85, v86, v172
	v_mov_b32_e32 v86, v83
	v_mul_f32_e32 v82, 0xbfb8aa3b, v85
	v_exp_f32_e32 v91, v82
	v_pk_mul_f32 v[82:83], v[86:87], v[172:173] op_sel_hi:[1,0]
	v_mul_f32_e32 v81, v81, v89
	v_mul_f32_e32 v86, 0xbfb8aa3b, v83
	v_exp_f32_e32 v86, v86
	v_add_f32_e32 v87, 1.0, v91
	v_rcp_f32_e32 v87, v87
	v_mul_f32_e32 v89, v80, v81
	v_add_f32_e32 v86, 1.0, v86
	v_rcp_f32_e32 v86, v86
	v_mul_f32_e32 v80, v85, v87
	v_mul_f32_e32 v84, v84, v80
	v_mul_f32_e32 v80, v83, v86
	v_mul_f32_e32 v86, v72, v170
	v_mul_f32_e32 v87, v76, v170
	v_mul_f32_e32 v83, v82, v80
	v_mul_f32_e32 v72, 0xbfb8aa3b, v87
	v_cvt_pk_bf16_f32 v80, v96, v95
	v_cvt_pk_bf16_f32 v81, v92, v90
	v_cvt_pk_bf16_f32 v82, v88, v89
	v_exp_f32_e32 v88, v72
	v_mov_b32_e32 v76, v73
	v_pk_mul_f32 v[72:73], v[76:77], v[170:171] op_sel_hi:[1,0]
	v_cvt_pk_bf16_f32 v83, v84, v83
	v_mad_i64_i32 v[84:85], s[4:5], v156, s51, v[112:113]
	v_mul_f32_e32 v76, 0xbfb8aa3b, v73
	v_exp_f32_e32 v89, v76
	v_lshl_add_u64 v[76:77], v[84:85], 0, v[114:115]
	v_add_f32_e32 v84, 1.0, v88
	v_rcp_f32_e32 v84, v84
	global_store_dwordx4 v[76:77], v[80:83], off
	v_add_f32_e32 v85, 1.0, v89
	v_mul_f32_e32 v76, v87, v84
	v_mul_f32_e32 v80, v86, v76
	v_mul_f32_e32 v76, v74, v170
	v_mul_f32_e32 v77, v78, v170
	v_mov_b32_e32 v78, v75
	v_mul_f32_e32 v74, 0xbfb8aa3b, v77
	v_rcp_f32_e32 v85, v85
	v_exp_f32_e32 v81, v74
	v_pk_mul_f32 v[74:75], v[78:79], v[170:171] op_sel_hi:[1,0]
	v_mul_f32_e32 v73, v73, v85
	v_mul_f32_e32 v78, 0xbfb8aa3b, v75
	v_exp_f32_e32 v78, v78
	v_mul_f32_e32 v79, v72, v73
	v_add_f32_e32 v72, 1.0, v81
	v_rcp_f32_e32 v81, v72
	v_add_f32_e32 v72, 1.0, v78
	v_rcp_f32_e32 v78, v72
	v_mul_f32_e32 v72, v64, v170
	v_mul_f32_e32 v73, v68, v170
	v_mul_f32_e32 v68, v77, v81
	v_mul_f32_e32 v64, 0xbfb8aa3b, v73
	v_exp_f32_e32 v64, v64
	v_mul_f32_e32 v76, v76, v68
	v_mov_b32_e32 v68, v65
	v_mul_f32_e32 v75, v75, v78
	v_add_f32_e32 v64, 1.0, v64
	v_rcp_f32_e32 v77, v64
	v_pk_mul_f32 v[64:65], v[68:69], v[170:171] op_sel_hi:[1,0]
	v_mul_f32_e32 v74, v74, v75
	v_mul_f32_e32 v68, 0xbfb8aa3b, v65
	v_exp_f32_e32 v68, v68
	v_mul_f32_e32 v69, v73, v77
	v_mul_f32_e32 v72, v72, v69
	v_add_f32_e32 v68, 1.0, v68
	v_rcp_f32_e32 v73, v68
	v_mul_f32_e32 v68, v66, v170
	v_mul_f32_e32 v69, v70, v170
	v_mov_b32_e32 v70, v67
	v_mul_f32_e32 v66, 0xbfb8aa3b, v69
	v_exp_f32_e32 v75, v66
	v_pk_mul_f32 v[66:67], v[70:71], v[170:171] op_sel_hi:[1,0]
	v_mul_f32_e32 v65, v65, v73
	v_mul_f32_e32 v70, 0xbfb8aa3b, v67
	v_exp_f32_e32 v70, v70
	v_add_f32_e32 v71, 1.0, v75
	v_rcp_f32_e32 v71, v71
	v_mul_f32_e32 v73, v64, v65
	v_add_f32_e32 v70, 1.0, v70
	v_rcp_f32_e32 v70, v70
	v_mul_f32_e32 v64, v69, v71
	v_mul_f32_e32 v68, v68, v64
	v_mul_f32_e32 v64, v67, v70
	v_mul_f32_e32 v70, v56, v168
	v_mul_f32_e32 v71, v60, v168
	v_mul_f32_e32 v67, v66, v64
	v_mul_f32_e32 v56, 0xbfb8aa3b, v71
	v_cvt_pk_bf16_f32 v64, v80, v79
	v_cvt_pk_bf16_f32 v65, v76, v74
	v_cvt_pk_bf16_f32 v66, v72, v73
	v_exp_f32_e32 v72, v56
	v_mov_b32_e32 v60, v57
	v_pk_mul_f32 v[56:57], v[60:61], v[168:169] op_sel_hi:[1,0]
	v_cvt_pk_bf16_f32 v67, v68, v67
	v_mad_i64_i32 v[68:69], s[4:5], v154, s51, v[112:113]
	v_mul_f32_e32 v60, 0xbfb8aa3b, v57
	v_exp_f32_e32 v73, v60
	v_lshl_add_u64 v[60:61], v[68:69], 0, v[114:115]
	v_add_f32_e32 v68, 1.0, v72
	v_rcp_f32_e32 v68, v68
	global_store_dwordx4 v[60:61], v[64:67], off
	v_add_f32_e32 v69, 1.0, v73
	v_mul_f32_e32 v60, v71, v68
	v_mul_f32_e32 v64, v70, v60
	v_mul_f32_e32 v60, v58, v168
	v_mul_f32_e32 v61, v62, v168
	v_mov_b32_e32 v62, v59
	v_mul_f32_e32 v58, 0xbfb8aa3b, v61
	v_rcp_f32_e32 v69, v69
	v_exp_f32_e32 v65, v58
	v_pk_mul_f32 v[58:59], v[62:63], v[168:169] op_sel_hi:[1,0]
	v_mul_f32_e32 v57, v57, v69
	v_mul_f32_e32 v62, 0xbfb8aa3b, v59
	v_exp_f32_e32 v62, v62
	v_mul_f32_e32 v63, v56, v57
	v_add_f32_e32 v56, 1.0, v65
	v_rcp_f32_e32 v65, v56
	v_add_f32_e32 v56, 1.0, v62
	v_rcp_f32_e32 v62, v56
	v_mul_f32_e32 v56, v48, v168
	v_mul_f32_e32 v57, v52, v168
	v_mul_f32_e32 v52, v61, v65
	v_mul_f32_e32 v48, 0xbfb8aa3b, v57
	v_exp_f32_e32 v48, v48
	v_mul_f32_e32 v60, v60, v52
	v_mov_b32_e32 v52, v49
	v_mul_f32_e32 v59, v59, v62
	v_add_f32_e32 v48, 1.0, v48
	v_rcp_f32_e32 v61, v48
	v_pk_mul_f32 v[48:49], v[52:53], v[168:169] op_sel_hi:[1,0]
	v_mul_f32_e32 v58, v58, v59
	v_mul_f32_e32 v52, 0xbfb8aa3b, v49
	v_exp_f32_e32 v52, v52
	v_mul_f32_e32 v53, v57, v61
	v_mul_f32_e32 v56, v56, v53
	v_add_f32_e32 v52, 1.0, v52
	v_rcp_f32_e32 v57, v52
	v_mul_f32_e32 v52, v50, v168
	v_mul_f32_e32 v53, v54, v168
	v_mov_b32_e32 v54, v51
	v_mul_f32_e32 v50, 0xbfb8aa3b, v53
	v_exp_f32_e32 v59, v50
	v_pk_mul_f32 v[50:51], v[54:55], v[168:169] op_sel_hi:[1,0]
	v_mul_f32_e32 v49, v49, v57
	v_mul_f32_e32 v54, 0xbfb8aa3b, v51
	v_exp_f32_e32 v54, v54
	v_add_f32_e32 v55, 1.0, v59
	v_rcp_f32_e32 v55, v55
	v_mul_f32_e32 v57, v48, v49
	v_add_f32_e32 v54, 1.0, v54
	v_rcp_f32_e32 v54, v54
	v_mul_f32_e32 v48, v53, v55
	v_mul_f32_e32 v52, v52, v48
	v_mul_f32_e32 v48, v51, v54
	v_mul_f32_e32 v54, v40, v166
	v_mul_f32_e32 v55, v44, v166
	v_mul_f32_e32 v51, v50, v48
	v_mul_f32_e32 v40, 0xbfb8aa3b, v55
	v_cvt_pk_bf16_f32 v48, v64, v63
	v_cvt_pk_bf16_f32 v49, v60, v58
	v_cvt_pk_bf16_f32 v50, v56, v57
	v_exp_f32_e32 v56, v40
	v_mov_b32_e32 v44, v41
	v_pk_mul_f32 v[40:41], v[44:45], v[166:167] op_sel_hi:[1,0]
	v_cvt_pk_bf16_f32 v51, v52, v51
	v_mad_i64_i32 v[52:53], s[4:5], v148, s51, v[112:113]
	v_mul_f32_e32 v44, 0xbfb8aa3b, v41
	v_exp_f32_e32 v57, v44
	v_lshl_add_u64 v[44:45], v[52:53], 0, v[114:115]
	v_add_f32_e32 v52, 1.0, v56
	v_rcp_f32_e32 v52, v52
	global_store_dwordx4 v[44:45], v[48:51], off
	v_add_f32_e32 v53, 1.0, v57
	v_mul_f32_e32 v44, v55, v52
	v_mul_f32_e32 v48, v54, v44
	v_mul_f32_e32 v44, v42, v166
	v_mul_f32_e32 v45, v46, v166
	v_mov_b32_e32 v46, v43
	v_mul_f32_e32 v42, 0xbfb8aa3b, v45
	v_rcp_f32_e32 v53, v53
	v_exp_f32_e32 v49, v42
	v_pk_mul_f32 v[42:43], v[46:47], v[166:167] op_sel_hi:[1,0]
	v_mul_f32_e32 v41, v41, v53
	v_mul_f32_e32 v46, 0xbfb8aa3b, v43
	v_exp_f32_e32 v46, v46
	v_mul_f32_e32 v47, v40, v41
	v_add_f32_e32 v40, 1.0, v49
	v_rcp_f32_e32 v49, v40
	v_add_f32_e32 v40, 1.0, v46
	v_rcp_f32_e32 v46, v40
	v_mul_f32_e32 v40, v32, v166
	v_mul_f32_e32 v41, v36, v166
	v_mul_f32_e32 v36, v45, v49
	v_mul_f32_e32 v32, 0xbfb8aa3b, v41
	v_exp_f32_e32 v32, v32
	v_mul_f32_e32 v44, v44, v36
	v_mov_b32_e32 v36, v33
	v_mul_f32_e32 v43, v43, v46
	v_add_f32_e32 v32, 1.0, v32
	v_rcp_f32_e32 v45, v32
	v_pk_mul_f32 v[32:33], v[36:37], v[166:167] op_sel_hi:[1,0]
	v_mul_f32_e32 v42, v42, v43
	v_mul_f32_e32 v36, 0xbfb8aa3b, v33
	v_exp_f32_e32 v36, v36
	v_mul_f32_e32 v37, v41, v45
	v_mul_f32_e32 v40, v40, v37
	v_add_f32_e32 v36, 1.0, v36
	v_rcp_f32_e32 v41, v36
	v_mul_f32_e32 v36, v34, v166
	v_mul_f32_e32 v37, v38, v166
	v_mov_b32_e32 v38, v35
	v_mul_f32_e32 v34, 0xbfb8aa3b, v37
	v_exp_f32_e32 v43, v34
	v_pk_mul_f32 v[34:35], v[38:39], v[166:167] op_sel_hi:[1,0]
	v_mul_f32_e32 v33, v33, v41
	v_mul_f32_e32 v38, 0xbfb8aa3b, v35
	v_exp_f32_e32 v38, v38
	v_add_f32_e32 v39, 1.0, v43
	v_rcp_f32_e32 v39, v39
	v_mul_f32_e32 v41, v32, v33
	v_add_f32_e32 v38, 1.0, v38
	v_rcp_f32_e32 v38, v38
	v_mul_f32_e32 v32, v37, v39
	v_mul_f32_e32 v36, v36, v32
	v_mul_f32_e32 v32, v35, v38
	v_mul_f32_e32 v38, v24, v164
	v_mul_f32_e32 v39, v28, v164
	v_mul_f32_e32 v35, v34, v32
	v_mul_f32_e32 v24, 0xbfb8aa3b, v39
	v_cvt_pk_bf16_f32 v32, v48, v47
	v_cvt_pk_bf16_f32 v33, v44, v42
	v_cvt_pk_bf16_f32 v34, v40, v41
	v_exp_f32_e32 v40, v24
	v_mov_b32_e32 v28, v25
	v_pk_mul_f32 v[24:25], v[28:29], v[164:165] op_sel_hi:[1,0]
	v_cvt_pk_bf16_f32 v35, v36, v35
	v_mad_i64_i32 v[36:37], s[4:5], v152, s51, v[112:113]
	v_mul_f32_e32 v28, 0xbfb8aa3b, v25
	v_exp_f32_e32 v41, v28
	v_lshl_add_u64 v[28:29], v[36:37], 0, v[114:115]
	v_add_f32_e32 v36, 1.0, v40
	v_rcp_f32_e32 v36, v36
	global_store_dwordx4 v[28:29], v[32:35], off
	v_add_f32_e32 v37, 1.0, v41
	v_mul_f32_e32 v28, v39, v36
	v_mul_f32_e32 v32, v38, v28
	v_mul_f32_e32 v28, v26, v164
	v_mul_f32_e32 v29, v30, v164
	v_mov_b32_e32 v30, v27
	v_mul_f32_e32 v26, 0xbfb8aa3b, v29
	v_rcp_f32_e32 v37, v37
	v_exp_f32_e32 v33, v26
	v_pk_mul_f32 v[26:27], v[30:31], v[164:165] op_sel_hi:[1,0]
	v_mul_f32_e32 v25, v25, v37
	v_mul_f32_e32 v30, 0xbfb8aa3b, v27
	v_exp_f32_e32 v30, v30
	v_mul_f32_e32 v31, v24, v25
	v_add_f32_e32 v24, 1.0, v33
	v_rcp_f32_e32 v33, v24
	v_add_f32_e32 v24, 1.0, v30
	v_rcp_f32_e32 v30, v24
	v_mul_f32_e32 v24, v16, v164
	v_mul_f32_e32 v25, v20, v164
	v_mul_f32_e32 v20, v29, v33
	v_mul_f32_e32 v16, 0xbfb8aa3b, v25
	v_exp_f32_e32 v16, v16
	v_mul_f32_e32 v28, v28, v20
	v_mov_b32_e32 v20, v17
	v_mul_f32_e32 v27, v27, v30
	v_add_f32_e32 v16, 1.0, v16
	v_rcp_f32_e32 v29, v16
	v_pk_mul_f32 v[16:17], v[20:21], v[164:165] op_sel_hi:[1,0]
	v_mul_f32_e32 v26, v26, v27
	v_mul_f32_e32 v20, 0xbfb8aa3b, v17
	v_exp_f32_e32 v20, v20
	v_mul_f32_e32 v21, v25, v29
	v_mul_f32_e32 v24, v24, v21
	v_add_f32_e32 v20, 1.0, v20
	v_rcp_f32_e32 v25, v20
	v_mul_f32_e32 v20, v18, v164
	v_mul_f32_e32 v21, v22, v164
	v_mov_b32_e32 v22, v19
	v_mul_f32_e32 v18, 0xbfb8aa3b, v21
	v_exp_f32_e32 v27, v18
	v_pk_mul_f32 v[18:19], v[22:23], v[164:165] op_sel_hi:[1,0]
	v_mul_f32_e32 v17, v17, v25
	v_mul_f32_e32 v22, 0xbfb8aa3b, v19
	v_exp_f32_e32 v22, v22
	v_add_f32_e32 v23, 1.0, v27
	v_rcp_f32_e32 v23, v23
	v_mul_f32_e32 v25, v16, v17
	v_add_f32_e32 v22, 1.0, v22
	v_rcp_f32_e32 v22, v22
	v_mul_f32_e32 v16, v21, v23
	v_mul_f32_e32 v20, v20, v16
	v_mul_f32_e32 v16, v19, v22
	v_mul_f32_e32 v22, v8, v158
	v_mul_f32_e32 v23, v12, v158
	v_mul_f32_e32 v19, v18, v16
	v_mul_f32_e32 v8, 0xbfb8aa3b, v23
	v_cvt_pk_bf16_f32 v16, v32, v31
	v_cvt_pk_bf16_f32 v17, v28, v26
	v_cvt_pk_bf16_f32 v18, v24, v25
	v_exp_f32_e32 v24, v8
	v_mov_b32_e32 v12, v9
	v_pk_mul_f32 v[8:9], v[12:13], v[158:159] op_sel_hi:[1,0]
	v_cvt_pk_bf16_f32 v19, v20, v19
	v_mad_i64_i32 v[20:21], s[4:5], v150, s51, v[112:113]
	v_mul_f32_e32 v12, 0xbfb8aa3b, v9
	v_exp_f32_e32 v25, v12
	v_lshl_add_u64 v[12:13], v[20:21], 0, v[114:115]
	v_add_f32_e32 v20, 1.0, v24
	v_rcp_f32_e32 v20, v20
	global_store_dwordx4 v[12:13], v[16:19], off
	v_add_f32_e32 v21, 1.0, v25
	v_mul_f32_e32 v12, v23, v20
	v_mul_f32_e32 v16, v22, v12
	v_mul_f32_e32 v12, v10, v158
	v_mul_f32_e32 v13, v14, v158
	v_mov_b32_e32 v14, v11
	v_mul_f32_e32 v10, 0xbfb8aa3b, v13
	v_rcp_f32_e32 v21, v21
	v_exp_f32_e32 v17, v10
	v_pk_mul_f32 v[10:11], v[14:15], v[158:159] op_sel_hi:[1,0]
	v_mul_f32_e32 v9, v9, v21
	v_mul_f32_e32 v14, 0xbfb8aa3b, v11
	v_exp_f32_e32 v14, v14
	v_mul_f32_e32 v15, v8, v9
	v_add_f32_e32 v8, 1.0, v17
	v_rcp_f32_e32 v17, v8
	v_add_f32_e32 v8, 1.0, v14
	v_rcp_f32_e32 v14, v8
	v_mul_f32_e32 v8, v0, v158
	v_mul_f32_e32 v9, v4, v158
	v_mul_f32_e32 v4, v13, v17
	v_mul_f32_e32 v0, 0xbfb8aa3b, v9
	v_exp_f32_e32 v0, v0
	v_mul_f32_e32 v12, v12, v4
	v_mov_b32_e32 v4, v1
	v_mul_f32_e32 v11, v11, v14
	v_add_f32_e32 v0, 1.0, v0
	v_rcp_f32_e32 v13, v0
	v_pk_mul_f32 v[0:1], v[4:5], v[158:159] op_sel_hi:[1,0]
	v_mul_f32_e32 v10, v10, v11
	v_mul_f32_e32 v4, 0xbfb8aa3b, v1
	v_exp_f32_e32 v4, v4
	v_mul_f32_e32 v5, v9, v13
	v_mul_f32_e32 v8, v8, v5
	v_add_f32_e32 v4, 1.0, v4
	v_rcp_f32_e32 v9, v4
	v_mul_f32_e32 v4, v2, v158
	v_mul_f32_e32 v5, v6, v158
	v_mov_b32_e32 v6, v3
	v_mul_f32_e32 v2, 0xbfb8aa3b, v5
	v_exp_f32_e32 v11, v2
	v_pk_mul_f32 v[2:3], v[6:7], v[158:159] op_sel_hi:[1,0]
	v_mul_f32_e32 v1, v1, v9
	v_mul_f32_e32 v6, 0xbfb8aa3b, v3
	v_exp_f32_e32 v6, v6
	v_add_f32_e32 v7, 1.0, v11
	v_rcp_f32_e32 v7, v7
	v_mul_f32_e32 v9, v0, v1
	v_add_f32_e32 v6, 1.0, v6
	v_rcp_f32_e32 v6, v6
	v_mul_f32_e32 v0, v5, v7
	v_mul_f32_e32 v4, v4, v0
	v_mul_f32_e32 v0, v3, v6
	v_mul_f32_e32 v3, v2, v0
	v_cvt_pk_bf16_f32 v0, v16, v15
	v_cvt_pk_bf16_f32 v1, v12, v10
	v_cvt_pk_bf16_f32 v2, v8, v9
	v_cvt_pk_bf16_f32 v3, v4, v3
	v_mad_i64_i32 v[4:5], s[4:5], v146, s51, v[112:113]
	v_lshl_add_u64 v[4:5], v[4:5], 0, v[114:115]
	s_mov_b64 s[4:5], -1
	global_store_dwordx4 v[4:5], v[0:3], off
	s_cbranch_vccnz .LBB0_1044
	s_andn2_b64 vcc, exec, s[16:17]
	s_cbranch_vccnz .LBB0_1043
	s_mov_b32 s90, 1
	s_branch .LBB0_1043
